# v10 plus next-key-block K fragment prefetch in the NA and SWA attention loops
# baseline (speedup 1.0000x reference)
.LBB0_246:
	s_or_b64 exec, exec, s[0:1]
	v_lshrrev_b32_e32 v0, 3, v69
	v_and_b32_e32 v1, 4, v69
	v_and_or_b32 v0, v0, 56, v1
	v_lshrrev_b32_e32 v0, 1, v0
	v_or_b32_e32 v77, v0, v92
	v_lshlrev_b32_e32 v1, 4, v69
	v_sub_u32_e64 v2, v0, 4 clamp
	v_sub_u32_e64 v0, v0, 3 clamp
	v_and_b32_e32 v36, 48, v1
	v_ashrrev_i32_e32 v35, 9, v69
	v_min_u32_e32 v96, 24, v2
	v_min_u32_e32 v0, 24, v0
	v_or_b32_e32 v32, v36, v93
	v_lshlrev_b32_e32 v1, 6, v77
	v_lshlrev_b32_e32 v34, 11, v35
	v_sub_u32_e32 v0, v0, v96
	v_or3_b32 v80, v1, v34, v32
	v_lshlrev_b32_e32 v1, 6, v33
	v_add_u32_e32 v97, 8, v0
	v_mov_b32_e32 v15, 0
	v_ashrrev_i32_e32 v81, 31, v80
	v_cmp_lt_i32_e32 vcc, 0, v97
	v_lshlrev_b32_e32 v82, 1, v1
	v_mov_b32_e32 v14, v15
	v_mov_b32_e32 v13, v15
	v_mov_b32_e32 v12, v15
	v_mov_b32_e32 v11, v15
	v_mov_b32_e32 v10, v15
	v_mov_b32_e32 v9, v15
	v_mov_b32_e32 v8, v15
	v_mov_b32_e32 v7, v15
	v_mov_b32_e32 v6, v15
	v_mov_b32_e32 v5, v15
	v_mov_b32_e32 v4, v15
	v_mov_b32_e32 v3, v15
	v_mov_b32_e32 v2, v15
	v_mov_b32_e32 v1, v15
	v_mov_b32_e32 v0, v15
	v_mov_b32_e32 v31, v15
	v_mov_b32_e32 v30, v15
	v_mov_b32_e32 v29, v15
	v_mov_b32_e32 v28, v15
	v_mov_b32_e32 v27, v15
	v_mov_b32_e32 v26, v15
	v_mov_b32_e32 v25, v15
	v_mov_b32_e32 v24, v15
	v_mov_b32_e32 v23, v15
	v_mov_b32_e32 v22, v15
	v_mov_b32_e32 v21, v15
	v_mov_b32_e32 v20, v15
	v_mov_b32_e32 v19, v15
	v_mov_b32_e32 v18, v15
	v_mov_b32_e32 v17, v15
	v_mov_b32_e32 v16, v15
	v_mov_b32_e32 v117, v15
	s_waitcnt lgkmcnt(0)
	s_and_saveexec_b64 s[2:3], vcc
	s_cbranch_execz .LBB0_243
	v_writelane_b32 v254, s2, 57
	v_max_i32_e32 v0, 4, v77
	v_add_u32_e32 v3, -4, v0
	v_writelane_b32 v254, s3, 58
	v_writelane_b32 v254, s16, 59
	v_mov_b32_e32 v83, v65
	v_mov_b32_e32 v75, v65
	v_writelane_b32 v254, s17, 60
	v_sub_u32_e64 v2, v36, 8 clamp
	v_readlane_b32 s0, v254, 49
	v_readlane_b32 s1, v254, 50
	v_min_u32_e32 v98, 24, v3
	v_mov_b32_e32 v117, 0
	v_mov_b64_e32 v[0:1], s[0:1]
	v_mad_i64_i32 v[0:1], s[0:1], v80, s89, v[0:1]
	v_lshl_add_u64 v[0:1], v[0:1], 0, v[82:83]
	v_lshl_add_u64 v[0:1], v[0:1], 0, v[74:75]
	global_load_dwordx4 v[48:51], v[0:1], off
	global_load_dwordx4 v[52:55], v[0:1], off offset:32
	global_load_dwordx4 v[56:59], v[0:1], off offset:64
	global_load_dwordx4 v[60:63], v[0:1], off offset:96
	v_min_u32_e32 v75, 32, v2
	v_or_b32_e32 v4, v75, v68
	v_max_i32_e32 v2, 8, v32
	v_sub_u32_e32 v5, v4, v32
	v_add_u32_e32 v2, -8, v2
	v_max_i32_e32 v5, -15, v5
	v_min_u32_e32 v2, 48, v2
	v_add_u32_e32 v5, 15, v5
	v_add_u32_e32 v3, 16, v2
	v_min_u32_e32 v101, 30, v5
	v_or_b32_e32 v5, 1, v4
	v_cmp_ge_u32_e64 s[6:7], v5, v2
	v_cmp_lt_u32_e64 s[8:9], v5, v3
	v_sub_u32_e32 v5, v5, v32
	v_max_i32_e32 v5, -15, v5
	v_add_u32_e32 v5, 15, v5
	v_min_u32_e32 v102, 30, v5
	v_or_b32_e32 v5, 2, v4
	v_cmp_ge_u32_e64 s[10:11], v5, v2
	v_cmp_lt_u32_e64 s[12:13], v5, v3
	v_sub_u32_e32 v5, v5, v32
	v_max_i32_e32 v5, -15, v5
	v_add_u32_e32 v5, 15, v5
	v_min_u32_e32 v103, 30, v5
	v_or_b32_e32 v5, 3, v4
	v_cmp_ge_u32_e64 s[14:15], v5, v2
	v_cmp_lt_u32_e64 s[16:17], v5, v3
	v_sub_u32_e32 v5, v5, v32
	v_max_i32_e32 v5, -15, v5
	v_add_u32_e32 v5, 15, v5
	v_min_u32_e32 v104, 30, v5
	v_add_u32_e32 v5, 8, v4
	v_cmp_ge_u32_e64 s[18:19], v5, v2
	v_cmp_lt_u32_e64 s[20:21], v5, v3
	v_sub_u32_e32 v5, v5, v32
	v_max_i32_e32 v5, -15, v5
	v_add_u32_e32 v5, 15, v5
	v_min_u32_e32 v105, 30, v5
	v_add_u32_e32 v5, 9, v4
	v_cmp_ge_u32_e64 s[22:23], v5, v2
	v_cmp_lt_u32_e64 s[24:25], v5, v3
	v_sub_u32_e32 v5, v5, v32
	v_max_i32_e32 v5, -15, v5
	v_add_u32_e32 v5, 15, v5
	v_min_u32_e32 v106, 30, v5
	v_add_u32_e32 v5, 10, v4
	v_cmp_ge_u32_e64 s[26:27], v5, v2
	v_cmp_lt_u32_e64 s[28:29], v5, v3
	v_sub_u32_e32 v5, v5, v32
	v_max_i32_e32 v5, -15, v5
	v_add_u32_e32 v5, 15, v5
	v_min_u32_e32 v107, 30, v5
	v_add_u32_e32 v5, 11, v4
	v_cmp_ge_u32_e64 s[30:31], v5, v2
	v_cmp_lt_u32_e64 s[34:35], v5, v3
	v_sub_u32_e32 v5, v5, v32
	v_max_i32_e32 v5, -15, v5
	v_add_u32_e32 v5, 15, v5
	v_min_u32_e32 v108, 30, v5
	v_add_u32_e32 v5, 16, v4
	v_cmp_ge_u32_e64 s[36:37], v5, v2
	v_sub_u32_e32 v5, v5, v32
	v_max_i32_e32 v5, -15, v5
	v_add_u32_e32 v5, 15, v5
	v_min_u32_e32 v109, 30, v5
	v_add_u32_e32 v5, 17, v4
	v_cmp_ge_u32_e64 s[40:41], v5, v2
	v_cmp_lt_u32_e64 s[42:43], v5, v3
	v_sub_u32_e32 v5, v5, v32
	v_max_i32_e32 v5, -15, v5
	v_add_u32_e32 v5, 15, v5
	v_min_u32_e32 v110, 30, v5
	v_add_u32_e32 v5, 18, v4
	v_cmp_ge_u32_e64 s[44:45], v5, v2
	v_cmp_lt_u32_e64 s[46:47], v5, v3
	v_sub_u32_e32 v5, v5, v32
	v_max_i32_e32 v5, -15, v5
	v_add_u32_e32 v5, 15, v5
	v_min_u32_e32 v111, 30, v5
	v_add_u32_e32 v5, 19, v4
	v_cmp_ge_u32_e64 s[48:49], v5, v2
	v_cmp_lt_u32_e64 s[50:51], v5, v3
	v_sub_u32_e32 v5, v5, v32
	v_max_i32_e32 v5, -15, v5
	v_add_u32_e32 v5, 15, v5
	v_min_u32_e32 v112, 30, v5
	v_add_u32_e32 v5, 24, v4
	v_cmp_ge_u32_e64 s[52:53], v5, v2
	v_cmp_lt_u32_e64 s[54:55], v5, v3
	v_sub_u32_e32 v5, v5, v32
	v_max_i32_e32 v5, -15, v5
	v_add_u32_e32 v5, 15, v5
	v_mad_i32_i24 v0, v35, 10, v33
	v_min_u32_e32 v113, 30, v5
	v_add_u32_e32 v5, 25, v4
	v_ashrrev_i32_e32 v1, 31, v0
	v_cmp_ge_u32_e64 s[56:57], v5, v2
	v_cmp_lt_u32_e64 s[58:59], v5, v3
	v_sub_u32_e32 v5, v5, v32
	v_lshlrev_b64 v[0:1], 18, v[0:1]
	v_max_i32_e32 v5, -15, v5
	v_lshl_add_u64 v[0:1], v[66:67], 0, v[0:1]
	s_mov_b64 s[0:1], 0x20000
	v_add_u32_e32 v5, 15, v5
	v_lshl_add_u64 v[84:85], v[0:1], 0, s[0:1]
	v_cmp_ge_u32_e64 s[0:1], v4, v2
	v_cmp_lt_u32_e64 s[4:5], v4, v3
	v_cmp_lt_u32_e64 s[38:39], v4, v2
	v_min_u32_e32 v114, 30, v5
	v_add_u32_e32 v5, 26, v4
	v_add_u32_e32 v4, 27, v4
	v_cmp_ge_u32_e64 s[60:61], v5, v2
	v_cmp_lt_u32_e64 s[62:63], v5, v3
	v_sub_u32_e32 v5, v5, v32
	v_cmp_ge_u32_e64 s[64:65], v4, v2
	v_sub_u32_e32 v2, v4, v32
	v_max_i32_e32 v5, -15, v5
	v_max_i32_e32 v2, -15, v2
	v_writelane_b32 v254, s0, 61
	v_add_u32_e32 v5, 15, v5
	v_add_u32_e32 v2, 15, v2
	v_or_b32_e32 v99, v34, v90
	v_add_u32_e32 v100, 8, v98
	v_writelane_b32 v254, s1, 62
	v_min_u32_e32 v115, 30, v5
	v_cmp_lt_u32_e64 s[66:67], v4, v3
	v_min_u32_e32 v116, 30, v2
	v_lshl_add_u64 v[86:87], v[72:73], 0, v[82:83]
	v_lshl_add_u64 v[88:89], v[0:1], 0, v[78:79]
	s_mov_b32 s33, 0
	v_mov_b32_e32 v83, 0xf149f2ca
	s_mov_b64 s[0:1], 0
	v_mov_b32_e32 v0, 0
	v_mov_b32_e32 v1, v117
	v_mov_b32_e32 v2, v117
	v_mov_b32_e32 v3, v117
	v_mov_b32_e32 v4, v117
	v_mov_b32_e32 v5, v117
	v_mov_b32_e32 v6, v117
	v_mov_b32_e32 v7, v117
	v_mov_b32_e32 v8, v117
	v_mov_b32_e32 v9, v117
	v_mov_b32_e32 v10, v117
	v_mov_b32_e32 v11, v117
	v_mov_b32_e32 v12, v117
	v_mov_b32_e32 v13, v117
	v_mov_b32_e32 v14, v117
	v_mov_b32_e32 v15, v117
	v_mov_b32_e32 v16, 0
	v_mov_b32_e32 v17, v117
	v_mov_b32_e32 v18, v117
	v_mov_b32_e32 v19, v117
	v_mov_b32_e32 v20, v117
	v_mov_b32_e32 v21, v117
	v_mov_b32_e32 v22, v117
	v_mov_b32_e32 v23, v117
	v_mov_b32_e32 v24, v117
	v_mov_b32_e32 v25, v117
	v_mov_b32_e32 v26, v117
	v_mov_b32_e32 v27, v117
	v_mov_b32_e32 v28, v117
	v_mov_b32_e32 v29, v117
	v_mov_b32_e32 v30, v117
	v_mov_b32_e32 v31, v117
	s_mov_b64 s[98:99], 0x88000
	v_add_u32_e32 v32, s33, v96
	v_lshl_or_b32 v64, v32, 6, v75
	v_sub_u32_e32 v33, v32, v77
	v_cmp_ge_u32_e32 vcc, v32, v98
	v_cmp_lt_u32_e64 s[68:69], v32, v100
	v_add_u32_e32 v32, v99, v64
	v_max_i32_e32 v33, -7, v33
	v_mad_i64_i32 v[36:37], s[2:3], v32, s89, v[86:87]
	global_load_dwordx4 v[200:203], v[36:37], off offset:1024
	global_load_dwordx4 v[204:207], v[36:37], off offset:1056
	global_load_dwordx4 v[208:211], v[36:37], off offset:1088
	global_load_dwordx4 v[212:215], v[36:37], off offset:1120
.LBB0_248:
	v_add_u32_e32 v32, s33, v96
	v_lshl_or_b32 v64, v32, 6, v75
	v_sub_u32_e32 v33, v32, v77
	v_cmp_ge_u32_e32 vcc, v32, v98
	v_cmp_lt_u32_e64 s[68:69], v32, v100
	v_add_u32_e32 v32, v99, v64
	v_max_i32_e32 v33, -7, v33
	v_mad_i64_i32 v[36:37], s[2:3], v32, s89, v[86:87]
	v_add_u32_e32 v38, 7, v33
	v_lshl_add_u64 v[218:219], v[36:37], 0, s[98:99]
	s_and_b64 s[84:85], vcc, s[68:69]
	v_min_u32_e32 v36, 14, v38
	s_movk_i32 vcc_lo, 0x7c
	v_mad_u32_u24 v130, v36, vcc_lo, v91
	v_lshl_add_u32 v131, v101, 2, v130
	v_lshl_add_u32 v132, v102, 2, v130
	ds_read_b32 v131, v131
	ds_read_b32 v132, v132
	v_readlane_b32 s2, v254, 61
	v_lshl_add_u32 v133, v103, 2, v130
	v_lshl_add_u32 v134, v104, 2, v130
	v_lshl_add_u32 v135, v105, 2, v130
	v_readlane_b32 s3, v254, 62
	v_lshl_add_u32 v136, v106, 2, v130
	v_lshl_add_u32 v137, v107, 2, v130
	v_lshl_add_u32 v138, v108, 2, v130
	v_lshl_add_u32 v139, v109, 2, v130
	s_and_b64 s[2:3], s[84:85], s[2:3]
	s_and_b64 s[96:97], s[84:85], s[6:7]
	s_and_b64 s[94:95], s[84:85], s[10:11]
	s_and_b64 s[92:93], s[84:85], s[14:15]
	s_and_b64 s[96:97], s[96:97], s[8:9]
	s_and_b64 s[2:3], s[2:3], s[4:5]
	s_and_b64 s[90:91], s[84:85], s[18:19]
	s_and_b64 s[88:89], s[84:85], s[22:23]
	v_lshl_add_u32 v140, v110, 2, v130
	v_lshl_add_u32 v141, v111, 2, v130
	v_lshl_add_u32 v142, v112, 2, v130
	v_lshl_add_u32 v143, v113, 2, v130
	v_lshl_add_u32 v144, v114, 2, v130
	v_lshl_add_u32 v145, v115, 2, v130
	v_lshl_add_u32 v130, v116, 2, v130
	s_and_b64 s[94:95], s[94:95], s[12:13]
	s_and_b64 s[92:93], s[92:93], s[16:17]
	s_and_b64 s[86:87], s[84:85], s[26:27]
	s_and_b64 s[68:69], s[84:85], s[30:31]
	s_and_b64 s[90:91], s[90:91], s[20:21]
	s_and_b64 s[88:89], s[88:89], s[24:25]
	s_and_b64 s[70:71], s[84:85], s[36:37]
	s_and_b64 s[72:73], s[84:85], s[40:41]
	s_and_b64 s[86:87], s[86:87], s[28:29]
	s_and_b64 s[68:69], s[68:69], s[34:35]
	s_and_b64 s[74:75], s[84:85], s[44:45]
	s_and_b64 s[76:77], s[84:85], s[48:49]
	s_and_b64 s[70:71], s[70:71], s[38:39]
	s_and_b64 s[72:73], s[72:73], s[42:43]
	s_and_b64 s[78:79], s[84:85], s[52:53]
	s_and_b64 s[80:81], s[84:85], s[56:57]
	s_and_b64 s[74:75], s[74:75], s[46:47]
	s_and_b64 s[76:77], s[76:77], s[50:51]
	s_and_b64 s[82:83], s[84:85], s[60:61]
	s_and_b64 s[84:85], s[84:85], s[64:65]
	s_and_b64 s[78:79], s[78:79], s[54:55]
	s_and_b64 s[80:81], s[80:81], s[58:59]
	s_and_b64 s[82:83], s[82:83], s[62:63]
	s_and_b64 s[84:85], s[84:85], s[66:67]
	s_add_i32 s33, s33, 1
	v_cmp_ge_i32_e32 vcc, s33, v97
	s_or_b64 s[0:1], vcc, s[0:1]
	s_waitcnt vmcnt(3)
	v_mfma_f32_32x32x16_bf16 v[32:47], v[200:203], v[48:51], 0
	s_waitcnt vmcnt(2)
	v_mfma_f32_32x32x16_bf16 v[32:47], v[204:207], v[52:55], v[32:47]
	ds_read_b32 v118, v133
	ds_read_b32 v119, v134
	ds_read_b32 v120, v135
	ds_read_b32 v121, v136
	ds_read_b32 v133, v137
	ds_read_b32 v134, v138
	ds_read_b32 v135, v139
	s_waitcnt vmcnt(1)
	v_mfma_f32_32x32x16_bf16 v[32:47], v[208:211], v[56:59], v[32:47]
	ds_read_b32 v122, v140
	ds_read_b32 v123, v141
	ds_read_b32 v124, v142
	ds_read_b32 v125, v143
	ds_read_b32 v136, v144
	ds_read_b32 v137, v145
	ds_read_b32 v130, v130
	s_waitcnt vmcnt(0)
	v_mfma_f32_32x32x16_bf16 v[32:47], v[212:215], v[60:63], v[32:47]
	s_waitcnt lgkmcnt(14)
	s_nop 10
	v_add_f32_e32 v32, v32, v131
	v_add_f32_e32 v33, v33, v132
	s_waitcnt lgkmcnt(13)
	v_add_f32_e32 v34, v34, v118
	s_waitcnt lgkmcnt(12)
	v_add_f32_e32 v118, v35, v119
	v_max_f32_e32 v35, 0xf149f2ca, v32
	s_waitcnt lgkmcnt(11)
	v_add_f32_e32 v119, v36, v120
	v_cndmask_b32_e64 v36, v95, v33, s[96:97]
	v_cndmask_b32_e64 v35, v95, v35, s[2:3]
	s_waitcnt lgkmcnt(10)
	v_add_f32_e32 v120, v37, v121
	s_waitcnt lgkmcnt(9)
	v_add_f32_e32 v121, v38, v133
	v_cndmask_b32_e64 v37, v95, v34, s[94:95]
	v_cndmask_b32_e64 v38, v95, v118, s[92:93]
	v_max_f32_e32 v35, v35, v36
	s_waitcnt lgkmcnt(8)
	v_add_f32_e32 v126, v39, v134
	s_waitcnt lgkmcnt(7)
	v_add_f32_e32 v127, v40, v135
	v_cndmask_b32_e64 v39, v95, v119, s[90:91]
	v_cndmask_b32_e64 v40, v95, v120, s[88:89]
	v_max3_f32 v35, v35, v37, v38
	s_waitcnt lgkmcnt(6)
	v_add_f32_e32 v122, v41, v122
	s_waitcnt lgkmcnt(5)
	v_add_f32_e32 v123, v42, v123
	v_cndmask_b32_e64 v41, v95, v121, s[86:87]
	v_cndmask_b32_e64 v42, v95, v126, s[68:69]
	v_max3_f32 v35, v35, v39, v40
	s_waitcnt lgkmcnt(4)
	v_add_f32_e32 v124, v43, v124
	s_waitcnt lgkmcnt(3)
	v_add_f32_e32 v125, v44, v125
	v_cndmask_b32_e64 v43, v95, v127, s[70:71]
	v_cndmask_b32_e64 v44, v95, v122, s[72:73]
	v_max3_f32 v35, v35, v41, v42
	s_waitcnt lgkmcnt(2)
	v_add_f32_e32 v128, v45, v136
	s_waitcnt lgkmcnt(1)
	v_add_f32_e32 v129, v46, v137
	v_cndmask_b32_e64 v45, v95, v123, s[74:75]
	v_cndmask_b32_e64 v46, v95, v124, s[76:77]
	v_max3_f32 v35, v35, v43, v44
	s_waitcnt lgkmcnt(0)
	v_add_f32_e32 v130, v47, v130
	v_cndmask_b32_e64 v47, v95, v125, s[78:79]
	v_cndmask_b32_e64 v131, v95, v128, s[80:81]
	v_max3_f32 v35, v35, v45, v46
	v_cndmask_b32_e64 v132, v95, v129, s[82:83]
	v_cndmask_b32_e64 v133, v95, v130, s[84:85]
	v_max3_f32 v35, v35, v47, v131
	v_max3_f32 v35, v35, v132, v133
	v_mov_b32_e32 v36, v35
	s_nop 1
	v_permlane32_swap_b32_e32 v35, v36
	v_max3_f32 v131, v83, v35, v36
	v_sub_f32_e32 v32, v32, v131
	v_mul_f32_e32 v32, 0x3fb8aa3b, v32
	v_exp_f32_e32 v32, v32
	v_mov_b32_e32 v135, v117
	v_sub_f32_e32 v117, v118, v131
	v_sub_f32_e32 v118, v119, v131
	v_cndmask_b32_e64 v132, 0, v32, s[2:3]
	v_sub_f32_e32 v32, v33, v131
	v_mul_f32_e32 v32, 0x3fb8aa3b, v32
	v_exp_f32_e32 v32, v32
	v_sub_f32_e32 v119, v120, v131
	v_sub_f32_e32 v120, v121, v131
	v_sub_f32_e32 v121, v126, v131
	v_cndmask_b32_e64 v133, 0, v32, s[96:97]
	v_sub_f32_e32 v32, v34, v131
	v_mul_f32_e32 v32, 0x3fb8aa3b, v32
	v_exp_f32_e32 v32, v32
	v_mul_f32_e32 v117, 0x3fb8aa3b, v117
	v_mul_f32_e32 v118, 0x3fb8aa3b, v118
	v_mul_f32_e32 v119, 0x3fb8aa3b, v119
	v_cndmask_b32_e64 v134, 0, v32, s[94:95]
	v_lshlrev_b64 v[32:33], 1, v[64:65]
	v_lshl_add_u64 v[38:39], v[88:89], 0, v[32:33]
	v_lshl_add_u64 v[36:37], v[84:85], 0, v[32:33]
	global_load_dwordx2 v[32:33], v[38:39], off
	global_load_dwordx2 v[34:35], v[38:39], off offset:16
	v_lshl_add_u64 v[46:47], v[36:37], 0, v[78:79]
	global_load_dwordx2 v[36:37], v[38:39], off offset:32
	s_nop 0
	global_load_dwordx2 v[38:39], v[38:39], off offset:48
	s_nop 0
	global_load_dwordx2 v[40:41], v[46:47], off
	global_load_dwordx2 v[42:43], v[46:47], off offset:16
	global_load_dwordx2 v[44:45], v[46:47], off offset:32
	s_nop 0
	global_load_dwordx2 v[46:47], v[46:47], off offset:48
	global_load_dwordx4 v[200:203], v[218:219], off offset:1024
	global_load_dwordx4 v[204:207], v[218:219], off offset:1056
	global_load_dwordx4 v[208:211], v[218:219], off offset:1088
	global_load_dwordx4 v[212:215], v[218:219], off offset:1120
	v_sub_f32_e32 v64, v83, v131
	v_mul_f32_e32 v120, 0x3fb8aa3b, v120
	v_mul_f32_e32 v121, 0x3fb8aa3b, v121
	v_mul_f32_e32 v64, 0x3fb8aa3b, v64
	v_exp_f32_e32 v117, v117
	v_exp_f32_e32 v118, v118
	v_exp_f32_e32 v119, v119
	v_exp_f32_e32 v120, v120
	v_exp_f32_e32 v121, v121
	v_exp_f32_e32 v64, v64
	v_sub_f32_e32 v126, v127, v131
	v_sub_f32_e32 v122, v122, v131
	v_sub_f32_e32 v123, v123, v131
	v_sub_f32_e32 v124, v124, v131
	v_sub_f32_e32 v125, v125, v131
	v_sub_f32_e32 v127, v128, v131
	v_sub_f32_e32 v128, v129, v131
	v_sub_f32_e32 v129, v130, v131
	v_mov_b32_e32 v83, v131
	v_cndmask_b32_e64 v117, 0, v117, s[92:93]
	v_cndmask_b32_e64 v130, 0, v118, s[90:91]
	v_cndmask_b32_e64 v131, 0, v119, s[88:89]
	v_cndmask_b32_e64 v136, 0, v120, s[86:87]
	v_cndmask_b32_e64 v137, 0, v121, s[68:69]
	v_pk_mul_f32 v[14:15], v[14:15], v[64:65] op_sel_hi:[1,0]
	v_pk_mul_f32 v[12:13], v[12:13], v[64:65] op_sel_hi:[1,0]
	v_pk_mul_f32 v[10:11], v[10:11], v[64:65] op_sel_hi:[1,0]
	v_pk_mul_f32 v[8:9], v[8:9], v[64:65] op_sel_hi:[1,0]
	v_pk_mul_f32 v[6:7], v[6:7], v[64:65] op_sel_hi:[1,0]
	v_pk_mul_f32 v[4:5], v[4:5], v[64:65] op_sel_hi:[1,0]
	v_pk_mul_f32 v[2:3], v[2:3], v[64:65] op_sel_hi:[1,0]
	v_pk_mul_f32 v[0:1], v[0:1], v[64:65] op_sel_hi:[1,0]
	v_cvt_pk_bf16_f32 v118, v132, v133
	v_cvt_pk_bf16_f32 v119, v134, v117
	v_cvt_pk_bf16_f32 v120, v130, v131
	v_cvt_pk_bf16_f32 v121, v136, v137
	v_mul_f32_e32 v126, 0x3fb8aa3b, v126
	v_mul_f32_e32 v122, 0x3fb8aa3b, v122
	s_waitcnt vmcnt(10)
	v_mfma_f32_32x32x16_bf16 v[0:15], v[32:35], v[118:121], v[0:15]
	v_mul_f32_e32 v123, 0x3fb8aa3b, v123
	v_mul_f32_e32 v124, 0x3fb8aa3b, v124
	v_mul_f32_e32 v125, 0x3fb8aa3b, v125
	v_mul_f32_e32 v127, 0x3fb8aa3b, v127
	v_mul_f32_e32 v128, 0x3fb8aa3b, v128
	v_mul_f32_e32 v129, 0x3fb8aa3b, v129
	v_exp_f32_e32 v126, v126
	v_exp_f32_e32 v122, v122
	v_exp_f32_e32 v123, v123
	v_exp_f32_e32 v124, v124
	v_exp_f32_e32 v125, v125
	v_exp_f32_e32 v127, v127
	v_exp_f32_e32 v128, v128
	v_exp_f32_e32 v129, v129
	v_pk_mul_f32 v[30:31], v[30:31], v[64:65] op_sel_hi:[1,0]
	v_pk_mul_f32 v[28:29], v[28:29], v[64:65] op_sel_hi:[1,0]
	v_pk_mul_f32 v[26:27], v[26:27], v[64:65] op_sel_hi:[1,0]
	v_pk_mul_f32 v[24:25], v[24:25], v[64:65] op_sel_hi:[1,0]
	v_pk_mul_f32 v[22:23], v[22:23], v[64:65] op_sel_hi:[1,0]
	v_pk_mul_f32 v[20:21], v[20:21], v[64:65] op_sel_hi:[1,0]
	v_pk_mul_f32 v[18:19], v[18:19], v[64:65] op_sel_hi:[1,0]
	v_pk_mul_f32 v[16:17], v[16:17], v[64:65] op_sel_hi:[1,0]
	v_cndmask_b32_e64 v126, 0, v126, s[70:71]
	v_cndmask_b32_e64 v122, 0, v122, s[72:73]
	s_waitcnt vmcnt(6)
	v_mfma_f32_32x32x16_bf16 v[16:31], v[40:43], v[118:121], v[16:31]
	v_add_f32_e32 v40, 0, v132
	v_cndmask_b32_e64 v123, 0, v123, s[74:75]
	v_cndmask_b32_e64 v124, 0, v124, s[76:77]
	v_cndmask_b32_e64 v125, 0, v125, s[78:79]
	v_cndmask_b32_e64 v127, 0, v127, s[80:81]
	v_cndmask_b32_e64 v128, 0, v128, s[82:83]
	v_cndmask_b32_e64 v129, 0, v129, s[84:85]
	v_add_f32_e32 v40, v133, v40
	v_cvt_pk_bf16_f32 v32, v126, v122
	v_cvt_pk_bf16_f32 v33, v123, v124
	v_cvt_pk_bf16_f32 v34, v125, v127
	v_cvt_pk_bf16_f32 v35, v128, v129
	v_add_f32_e32 v40, v134, v40
	s_movk_i32 s89, 0x2200
	v_mfma_f32_32x32x16_bf16 v[0:15], v[36:39], v[32:35], v[0:15]
	v_add_f32_e32 v36, v117, v40
	v_add_f32_e32 v36, v130, v36
	v_add_f32_e32 v36, v131, v36
	v_add_f32_e32 v36, v136, v36
	v_add_f32_e32 v36, v137, v36
	v_add_f32_e32 v36, v126, v36
	v_add_f32_e32 v36, v122, v36
	s_waitcnt vmcnt(4)
	v_mfma_f32_32x32x16_bf16 v[16:31], v[44:47], v[32:35], v[16:31]
	v_add_f32_e32 v32, v123, v36
	v_add_f32_e32 v32, v124, v32
	v_add_f32_e32 v32, v125, v32
	v_add_f32_e32 v32, v127, v32
	v_add_f32_e32 v32, v128, v32
	v_add_f32_e32 v117, v129, v32
	v_fmac_f32_e32 v117, v135, v64
	s_andn2_b64 exec, exec, s[0:1]
	s_cbranch_execnz .LBB0_248
	s_or_b64 exec, exec, s[0:1]
	v_readlane_b32 s68, v254, 25
	v_readlane_b32 s72, v254, 29
	v_readlane_b32 s73, v254, 30
	v_readlane_b32 s70, v254, 27
	v_readlane_b32 s71, v254, 28
	v_readlane_b32 s82, v254, 39
	v_readlane_b32 s83, v254, 40
	v_readlane_b32 s90, v254, 45
	v_readlane_b32 s86, v254, 47
	v_readlane_b32 s72, v254, 51
	v_readlane_b32 s16, v254, 59
	v_readlane_b32 s20, v254, 53
	v_readlane_b32 s22, v254, 55
	v_readlane_b32 s2, v254, 57
	s_mov_b64 s[70:71], s[82:83]
	v_readlane_b32 s91, v254, 46
	s_mov_b32 s88, s86
	s_mov_b32 s84, s72
	v_readlane_b32 s17, v254, 60
	v_readlane_b32 s21, v254, 54
	v_readlane_b32 s23, v254, 56
	v_readlane_b32 s3, v254, 58
	v_readlane_b32 s69, v254, 26
	v_readlane_b32 s74, v254, 31
	v_readlane_b32 s75, v254, 32
	v_readlane_b32 s76, v254, 33
	v_readlane_b32 s77, v254, 34
	v_readlane_b32 s78, v254, 35
	v_readlane_b32 s79, v254, 36
	v_readlane_b32 s80, v254, 37
	v_readlane_b32 s81, v254, 38
	v_readlane_b32 s87, v254, 48
	v_readlane_b32 s73, v254, 52
	s_branch .LBB0_243

.LBB0_253:
	v_lshrrev_b32_e32 v0, 3, v88
	v_and_b32_e32 v2, 4, v88
	v_and_b32_e32 v1, 6, v0
	v_and_or_b32 v0, v0, 8, v2
	v_lshrrev_b32_e32 v2, 1, v88
	v_ashrrev_i32_e32 v33, 8, v88
	v_and_b32_e32 v34, 4, v2
	v_lshrrev_b32_e32 v0, 2, v0
	v_and_or_b32 v35, v33, -8, v1
	v_and_b32_e32 v1, 0x780, v88
	v_or_b32_e32 v36, v0, v34
	v_lshlrev_b32_e32 v0, 5, v88
	v_and_or_b32 v0, v0, s54, v1
	v_lshlrev_b32_e32 v1, 10, v35
	v_or3_b32 v78, v0, v89, v1
	v_lshrrev_b32_e32 v0, 5, v0
	v_min_u32_e32 v2, 59, v0
	v_lshlrev_b32_e32 v1, 6, v36
	v_sub_u32_e64 v71, v0, 4 clamp
	v_add_u32_e32 v73, 5, v2
	v_ashrrev_i32_e32 v79, 31, v78
	v_cmp_lt_u32_e32 vcc, v71, v73
	v_lshlrev_b32_e32 v80, 1, v1
	v_mov_b32_e32 v15, v65
	v_mov_b32_e32 v14, v65
	v_mov_b32_e32 v13, v65
	v_mov_b32_e32 v12, v65
	v_mov_b32_e32 v11, v65
	v_mov_b32_e32 v10, v65
	v_mov_b32_e32 v9, v65
	v_mov_b32_e32 v8, v65
	v_mov_b32_e32 v7, v65
	v_mov_b32_e32 v6, v65
	v_mov_b32_e32 v5, v65
	v_mov_b32_e32 v4, v65
	v_mov_b32_e32 v3, v65
	v_mov_b32_e32 v2, v65
	v_mov_b32_e32 v1, v65
	v_mov_b32_e32 v0, v65
	v_mov_b32_e32 v31, v65
	v_mov_b32_e32 v30, v65
	v_mov_b32_e32 v29, v65
	v_mov_b32_e32 v28, v65
	v_mov_b32_e32 v27, v65
	v_mov_b32_e32 v26, v65
	v_mov_b32_e32 v25, v65
	v_mov_b32_e32 v24, v65
	v_mov_b32_e32 v23, v65
	v_mov_b32_e32 v22, v65
	v_mov_b32_e32 v21, v65
	v_mov_b32_e32 v20, v65
	v_mov_b32_e32 v19, v65
	v_mov_b32_e32 v18, v65
	v_mov_b32_e32 v17, v65
	v_mov_b32_e32 v16, v65
	v_mov_b32_e32 v32, v90
	s_and_saveexec_b64 s[48:49], vcc
	s_cbranch_execz .LBB0_252
	v_mov_b64_e32 v[0:1], s[38:39]
	v_mad_i64_i32 v[0:1], s[0:1], v78, s55, v[0:1]
	v_mov_b32_e32 v81, v65
	v_lshl_add_u64 v[0:1], v[0:1], 0, v[80:81]
	v_mov_b32_e32 v77, v65
	v_lshl_add_u64 v[0:1], v[0:1], 0, v[76:77]
	global_load_dwordx4 v[48:51], v[0:1], off offset:3072
	global_load_dwordx4 v[52:55], v[0:1], off offset:3104
	global_load_dwordx4 v[56:59], v[0:1], off offset:3136
	global_load_dwordx4 v[60:63], v[0:1], off offset:3168
	v_readlane_b32 s0, v254, 6
	v_lshlrev_b32_e32 v0, 2, v36
	v_readlane_b32 s12, v254, 18
	v_readlane_b32 s13, v254, 19
	v_lshrrev_b32_e32 v1, 1, v35
	v_mul_i32_i24_e32 v1, 10, v1
	v_mov_b32_e32 v69, v65
	v_lshlrev_b32_e32 v64, 5, v34
	v_lshl_add_u64 v[82:83], s[38:39], 0, v[64:65]
	global_load_dword v81, v0, s[12:13]
	v_and_b32_e32 v0, 0x60, v92
	v_and_or_b32 v2, v88, s53, v0
	v_lshrrev_b32_e32 v0, 5, v2
	v_min_u32_e32 v0, 4, v0
	v_lshlrev_b32_e32 v3, 5, v0
	v_lshlrev_b32_e32 v0, 7, v88
	v_and_b32_e32 v5, 0x1800, v0
	v_lshrrev_b32_e32 v0, 2, v34
	v_or_b32_e32 v0, v1, v0
	v_add_u32_e32 v0, 8, v0
	v_ashrrev_i32_e32 v1, 31, v0
	v_lshlrev_b64 v[0:1], 18, v[0:1]
	v_lshl_add_u64 v[0:1], v[66:67], 0, v[0:1]
	v_lshl_add_u64 v[84:85], v[0:1], 0, v[68:69]
	v_lshlrev_b32_e32 v0, 10, v33
	v_and_b32_e32 v0, 0xffffe000, v0
	v_or3_b32 v0, v0, v5, v2
	v_sub_u32_e32 v4, v2, v3
	v_sub_u32_e32 v69, v0, v3
	v_mov_b32_e32 v0, 0
	v_add_u32_e32 v75, v91, v3
	v_lshl_add_u64 v[86:87], v[84:85], 0, s[40:41]
	s_mov_b64 s[50:51], 0
	v_mov_b32_e32 v64, v4
	v_mov_b32_e32 v32, v90
	v_mov_b32_e32 v1, v0
	v_mov_b32_e32 v2, v0
	v_mov_b32_e32 v3, v0
	v_mov_b32_e32 v4, v0
	v_mov_b32_e32 v5, v0
	v_mov_b32_e32 v6, v0
	v_mov_b32_e32 v7, v0
	v_mov_b32_e32 v8, v0
	v_mov_b32_e32 v9, v0
	v_mov_b32_e32 v10, v0
	v_mov_b32_e32 v11, v0
	v_mov_b32_e32 v12, v0
	v_mov_b32_e32 v13, v0
	v_mov_b32_e32 v14, v0
	v_mov_b32_e32 v15, v0
	v_mov_b32_e32 v16, v0
	v_mov_b32_e32 v17, v0
	v_mov_b32_e32 v18, v0
	v_mov_b32_e32 v19, v0
	v_mov_b32_e32 v20, v0
	v_mov_b32_e32 v21, v0
	v_mov_b32_e32 v22, v0
	v_mov_b32_e32 v23, v0
	v_mov_b32_e32 v24, v0
	v_mov_b32_e32 v25, v0
	v_mov_b32_e32 v26, v0
	v_mov_b32_e32 v27, v0
	v_mov_b32_e32 v28, v0
	v_mov_b32_e32 v29, v0
	v_mov_b32_e32 v30, v0
	v_mov_b32_e32 v31, v0
	v_readlane_b32 s1, v254, 7
	v_readlane_b32 s2, v254, 8
	v_readlane_b32 s3, v254, 9
	v_readlane_b32 s4, v254, 10
	v_readlane_b32 s5, v254, 11
	v_readlane_b32 s6, v254, 12
	v_readlane_b32 s7, v254, 13
	v_readlane_b32 s8, v254, 14
	v_readlane_b32 s9, v254, 15
	v_readlane_b32 s10, v254, 16
	v_readlane_b32 s11, v254, 17
	v_readlane_b32 s14, v254, 20
	v_readlane_b32 s15, v254, 21
	s_mov_b64 s[98:99], 0x44000
	v_add_u32_e32 v216, v89, v69
	v_mad_i64_i32 v[216:217], s[0:1], v216, s55, v[82:83]
	v_lshl_add_u64 v[216:217], v[216:217], 0, v[76:77]
	v_add_co_u32_e64 v218, s[0:1], s33, v216
	v_lshl_add_u64 v[220:221], v[216:217], 0, s[42:43]
	s_nop 0
	v_addc_co_u32_e64 v219, s[0:1], 0, v217, s[0:1]
	global_load_dwordx4 v[200:203], v[218:219], off
	global_load_dwordx4 v[204:207], v[220:221], off offset:32
	global_load_dwordx4 v[208:211], v[220:221], off offset:64
	global_load_dwordx4 v[212:215], v[220:221], off offset:96
.LBB0_255:
	v_add_u32_e32 v36, v89, v69
	v_mov_b32_e32 v94, v32
	v_lshlrev_b64 v[32:33], 1, v[64:65]
	v_mad_i64_i32 v[36:37], s[0:1], v36, s55, v[82:83]
	v_add_u32_e32 v34, 16, v64
	v_mov_b32_e32 v35, v65
	v_lshl_add_u64 v[38:39], v[84:85], 0, v[32:33]
	v_lshl_add_u64 v[32:33], v[86:87], 0, v[32:33]
	v_lshl_add_u64 v[36:37], v[36:37], 0, v[76:77]
	v_lshl_add_u64 v[34:35], v[34:35], 1, v[86:87]
	global_load_dwordx2 v[96:97], v[38:39], off
	global_load_dwordx2 v[98:99], v[38:39], off offset:16
	global_load_dwordx2 v[100:101], v[38:39], off offset:32
	global_load_dwordx2 v[102:103], v[38:39], off offset:48
	global_load_dwordx2 v[104:105], v[32:33], off
	global_load_dwordx2 v[106:107], v[32:33], off offset:16
	global_load_dwordx2 v[108:109], v[34:35], off
	global_load_dwordx2 v[110:111], v[34:35], off offset:16
	v_add_co_u32_e64 v32, s[0:1], s33, v36
	v_lshl_add_u64 v[120:121], v[36:37], 0, s[42:43]
	s_nop 0
	v_addc_co_u32_e64 v33, s[0:1], 0, v37, s[0:1]
	v_lshl_add_u64 v[218:219], v[32:33], 0, s[98:99]
	s_nop 0
	v_lshl_add_u64 v[220:221], v[120:121], 0, s[98:99]
	v_add_u32_e32 v40, v89, v75
	v_sub_u32_e32 v41, 0, v40
	v_add_u32_e32 v42, -1, v40
	v_sub_u32_e32 v43, 1, v40
	v_add_u32_e32 v44, -2, v40
	v_sub_u32_e32 v45, 2, v40
	v_add_u32_e32 v95, -3, v40
	v_sub_u32_e32 v124, 3, v40
	v_add_u32_e32 v125, -8, v40
	v_sub_u32_e32 v126, 8, v40
	v_add_u32_e32 v127, -9, v40
	v_sub_u32_e32 v128, 9, v40
	v_add_u32_e32 v129, -10, v40
	v_sub_u32_e32 v130, 10, v40
	v_add_u32_e32 v131, -11, v40
	v_sub_u32_e32 v132, 11, v40
	v_add_u32_e32 v133, -16, v40
	v_sub_u32_e32 v134, 16, v40
	v_subrev_u32_e32 v135, 17, v40
	s_waitcnt vmcnt(19)
	v_sub_u32_e32 v136, 17, v40
	v_subrev_u32_e32 v137, 18, v40
	v_sub_u32_e32 v138, 18, v40
	v_subrev_u32_e32 v139, 19, v40
	s_waitcnt vmcnt(18)
	v_sub_u32_e32 v140, 19, v40
	v_subrev_u32_e32 v141, 24, v40
	v_sub_u32_e32 v142, 24, v40
	v_subrev_u32_e32 v143, 25, v40
	v_sub_u32_e32 v144, 25, v40
	v_subrev_u32_e32 v145, 26, v40
	v_sub_u32_e32 v146, 26, v40
	v_subrev_u32_e32 v147, 27, v40
	v_sub_u32_e32 v148, 27, v40
	v_max_i32_e32 v149, v40, v41
	v_max_i32_e32 v150, v42, v43
	v_max_i32_e32 v151, v44, v45
	v_add_u32_e32 v71, 1, v71
	v_cmp_ge_u32_e32 vcc, v71, v73
	v_max_i32_e32 v95, v95, v124
	s_or_b64 s[50:51], vcc, s[50:51]
	v_cmp_gt_u32_e32 vcc, s56, v150
	v_cmp_gt_u32_e64 s[2:3], s56, v95
	v_cmp_gt_u32_e64 s[28:29], s56, v149
	v_cmp_gt_u32_e64 s[0:1], s56, v151
	v_max_i32_e32 v124, v133, v134
	v_cmp_gt_u32_e64 s[12:13], s56, v124
	v_subrev_u32_e32 v75, 32, v75
	v_add_u32_e32 v64, 32, v64
	v_add_u32_e32 v69, 32, v69
	s_waitcnt vmcnt(11)
	v_mfma_f32_32x32x16_bf16 v[32:47], v[200:203], v[48:51], 0
	s_waitcnt vmcnt(10)
	v_mfma_f32_32x32x16_bf16 v[32:47], v[204:207], v[52:55], v[32:47]
	v_max_i32_e32 v112, v125, v126
	v_cmp_gt_u32_e64 s[4:5], s56, v112
	v_max_i32_e32 v113, v127, v128
	v_max_i32_e32 v114, v129, v130
	v_max_i32_e32 v115, v131, v132
	v_cmp_gt_u32_e64 s[6:7], s56, v113
	v_cmp_gt_u32_e64 s[8:9], s56, v114
	s_waitcnt vmcnt(8)
	v_mfma_f32_32x32x16_bf16 v[32:47], v[208:211], v[56:59], v[32:47]
	v_max_i32_e32 v125, v135, v136
	v_cmp_gt_u32_e64 s[10:11], s56, v115
	v_max_i32_e32 v120, v137, v138
	v_max_i32_e32 v121, v139, v140
	v_cmp_gt_u32_e64 s[14:15], s56, v125
	v_max_i32_e32 v122, v141, v142
	v_max_i32_e32 v123, v143, v144
	v_mfma_f32_32x32x16_bf16 v[32:47], v[212:215], v[60:63], v[32:47]
	global_load_dwordx4 v[200:203], v[218:219], off
	global_load_dwordx4 v[204:207], v[220:221], off offset:32
	global_load_dwordx4 v[208:211], v[220:221], off offset:64
	global_load_dwordx4 v[212:215], v[220:221], off offset:96
	v_cmp_gt_u32_e64 s[16:17], s56, v120
	v_cmp_gt_u32_e64 s[18:19], s56, v121
	v_max_i32_e32 v126, v145, v146
	v_max_i32_e32 v127, v147, v148
	v_cmp_gt_u32_e64 s[20:21], s56, v122
	v_cmp_gt_u32_e64 s[22:23], s56, v123
	v_cmp_gt_u32_e64 s[24:25], s56, v126
	s_nop 4
	v_max_f32_e32 v95, v32, v32
	v_cndmask_b32_e32 v112, v93, v33, vcc
	v_max_f32_e32 v95, 0xf149f2ca, v95
	v_max_f32_e32 v112, v112, v112
	v_cndmask_b32_e64 v95, v93, v95, s[28:29]
	v_cndmask_b32_e64 v113, v93, v34, s[0:1]
	v_cndmask_b32_e64 v114, v93, v35, s[2:3]
	v_max_f32_e32 v95, v95, v112
	v_cndmask_b32_e64 v115, v93, v36, s[4:5]
	v_cndmask_b32_e64 v116, v93, v37, s[6:7]
	v_max3_f32 v95, v95, v113, v114
	v_cndmask_b32_e64 v117, v93, v38, s[8:9]
	v_cndmask_b32_e64 v118, v93, v39, s[10:11]
	v_max3_f32 v95, v95, v115, v116
	v_cndmask_b32_e64 v119, v93, v40, s[12:13]
	v_cndmask_b32_e64 v120, v93, v41, s[14:15]
	v_max3_f32 v95, v95, v117, v118
	v_cndmask_b32_e64 v121, v93, v42, s[16:17]
	v_cndmask_b32_e64 v122, v93, v43, s[18:19]
	v_max3_f32 v95, v95, v119, v120
	v_cmp_gt_u32_e64 s[26:27], s56, v127
	v_cndmask_b32_e64 v123, v93, v44, s[20:21]
	v_cndmask_b32_e64 v124, v93, v45, s[22:23]
	v_max3_f32 v95, v95, v121, v122
	v_cndmask_b32_e64 v125, v93, v46, s[24:25]
	v_cndmask_b32_e64 v126, v93, v47, s[26:27]
	v_max3_f32 v95, v95, v123, v124
	v_max3_f32 v95, v95, v125, v126
	v_mov_b32_e32 v112, v95
	s_nop 1
	v_permlane32_swap_b32_e32 v95, v112
	v_max3_f32 v95, v81, v95, v112
	v_sub_f32_e32 v32, v32, v95
	v_sub_f32_e32 v33, v33, v95
	v_sub_f32_e32 v34, v34, v95
	v_sub_f32_e32 v35, v35, v95
	v_sub_f32_e32 v36, v36, v95
	v_sub_f32_e32 v37, v37, v95
	v_sub_f32_e32 v38, v38, v95
	v_sub_f32_e32 v39, v39, v95
	v_sub_f32_e32 v112, v81, v95
	v_mul_f32_e32 v32, 0x3fb8aa3b, v32
	v_mul_f32_e32 v33, 0x3fb8aa3b, v33
	v_mul_f32_e32 v34, 0x3fb8aa3b, v34
	v_mul_f32_e32 v35, 0x3fb8aa3b, v35
	v_mul_f32_e32 v36, 0x3fb8aa3b, v36
	v_mul_f32_e32 v37, 0x3fb8aa3b, v37
	v_mul_f32_e32 v38, 0x3fb8aa3b, v38
	v_mul_f32_e32 v39, 0x3fb8aa3b, v39
	v_sub_f32_e32 v40, v40, v95
	v_sub_f32_e32 v41, v41, v95
	v_sub_f32_e32 v42, v42, v95
	v_sub_f32_e32 v43, v43, v95
	v_sub_f32_e32 v44, v44, v95
	v_sub_f32_e32 v45, v45, v95
	v_sub_f32_e32 v46, v46, v95
	v_sub_f32_e32 v47, v47, v95
	v_mov_b32_e32 v81, v95
	v_mul_f32_e32 v95, 0x3fb8aa3b, v112
	v_exp_f32_e32 v32, v32
	v_exp_f32_e32 v33, v33
	v_exp_f32_e32 v34, v34
	v_exp_f32_e32 v35, v35
	v_exp_f32_e32 v112, v36
	v_exp_f32_e32 v37, v37
	v_exp_f32_e32 v38, v38
	v_exp_f32_e32 v39, v39
	v_exp_f32_e32 v36, v95
	v_cndmask_b32_e64 v95, 0, v32, s[28:29]
	v_cndmask_b32_e32 v113, 0, v33, vcc
	v_cndmask_b32_e64 v114, 0, v34, s[0:1]
	v_cndmask_b32_e64 v115, 0, v35, s[2:3]
	v_cndmask_b32_e64 v112, 0, v112, s[4:5]
	v_cndmask_b32_e64 v37, 0, v37, s[6:7]
	v_cndmask_b32_e64 v38, 0, v38, s[8:9]
	v_cndmask_b32_e64 v39, 0, v39, s[10:11]
	v_pk_mul_f32 v[14:15], v[14:15], v[36:37] op_sel_hi:[1,0]
	v_pk_mul_f32 v[12:13], v[12:13], v[36:37] op_sel_hi:[1,0]
	v_pk_mul_f32 v[10:11], v[10:11], v[36:37] op_sel_hi:[1,0]
	v_pk_mul_f32 v[8:9], v[8:9], v[36:37] op_sel_hi:[1,0]
	v_pk_mul_f32 v[6:7], v[6:7], v[36:37] op_sel_hi:[1,0]
	v_pk_mul_f32 v[4:5], v[4:5], v[36:37] op_sel_hi:[1,0]
	v_pk_mul_f32 v[2:3], v[2:3], v[36:37] op_sel_hi:[1,0]
	v_pk_mul_f32 v[0:1], v[0:1], v[36:37] op_sel_hi:[1,0]
	v_pk_mul_f32 v[30:31], v[30:31], v[36:37] op_sel_hi:[1,0]
	v_cvt_pk_bf16_f32 v32, v95, v113
	v_cvt_pk_bf16_f32 v33, v114, v115
	v_cvt_pk_bf16_f32 v34, v112, v37
	v_cvt_pk_bf16_f32 v35, v38, v39
	v_pk_mul_f32 v[28:29], v[28:29], v[36:37] op_sel_hi:[1,0]
	v_pk_mul_f32 v[26:27], v[26:27], v[36:37] op_sel_hi:[1,0]
	v_pk_mul_f32 v[24:25], v[24:25], v[36:37] op_sel_hi:[1,0]
	v_pk_mul_f32 v[22:23], v[22:23], v[36:37] op_sel_hi:[1,0]
	v_pk_mul_f32 v[20:21], v[20:21], v[36:37] op_sel_hi:[1,0]
	v_pk_mul_f32 v[18:19], v[18:19], v[36:37] op_sel_hi:[1,0]
	v_pk_mul_f32 v[16:17], v[16:17], v[36:37] op_sel_hi:[1,0]
	v_add_f32_e32 v95, 0, v95
	s_waitcnt vmcnt(10)
	v_mfma_f32_32x32x16_bf16 v[0:15], v[96:99], v[32:35], v[0:15]
	v_add_f32_e32 v95, v113, v95
	v_mul_f32_e32 v40, 0x3fb8aa3b, v40
	v_mul_f32_e32 v41, 0x3fb8aa3b, v41
	v_mul_f32_e32 v42, 0x3fb8aa3b, v42
	v_mul_f32_e32 v43, 0x3fb8aa3b, v43
	v_mul_f32_e32 v44, 0x3fb8aa3b, v44
	v_mul_f32_e32 v45, 0x3fb8aa3b, v45
	s_waitcnt vmcnt(6)
	v_mfma_f32_32x32x16_bf16 v[16:31], v[104:107], v[32:35], v[16:31]
	v_mul_f32_e32 v46, 0x3fb8aa3b, v46
	v_mul_f32_e32 v47, 0x3fb8aa3b, v47
	v_add_f32_e32 v95, v114, v95
	v_exp_f32_e32 v40, v40
	v_exp_f32_e32 v41, v41
	v_exp_f32_e32 v42, v42
	v_exp_f32_e32 v43, v43
	v_exp_f32_e32 v44, v44
	v_exp_f32_e32 v45, v45
	v_exp_f32_e32 v46, v46
	v_exp_f32_e32 v47, v47
	v_add_f32_e32 v95, v115, v95
	v_add_f32_e32 v95, v112, v95
	v_add_f32_e32 v37, v37, v95
	v_add_f32_e32 v37, v38, v37
	v_cndmask_b32_e64 v40, 0, v40, s[12:13]
	v_cndmask_b32_e64 v41, 0, v41, s[14:15]
	v_cndmask_b32_e64 v42, 0, v42, s[16:17]
	v_cndmask_b32_e64 v43, 0, v43, s[18:19]
	v_cndmask_b32_e64 v44, 0, v44, s[20:21]
	v_cndmask_b32_e64 v45, 0, v45, s[22:23]
	v_cndmask_b32_e64 v46, 0, v46, s[24:25]
	v_cndmask_b32_e64 v47, 0, v47, s[26:27]
	v_add_f32_e32 v37, v39, v37
	v_cvt_pk_bf16_f32 v32, v40, v41
	v_cvt_pk_bf16_f32 v33, v42, v43
	v_cvt_pk_bf16_f32 v34, v44, v45
	v_cvt_pk_bf16_f32 v35, v46, v47
	v_add_f32_e32 v37, v40, v37
	v_add_f32_e32 v37, v41, v37
	s_waitcnt vmcnt(6)
	v_mfma_f32_32x32x16_bf16 v[0:15], v[100:103], v[32:35], v[0:15]
	s_waitcnt vmcnt(4)
	v_mfma_f32_32x32x16_bf16 v[16:31], v[108:111], v[32:35], v[16:31]
	v_add_f32_e32 v32, v42, v37
	v_add_f32_e32 v32, v43, v32
	v_add_f32_e32 v32, v44, v32
	v_add_f32_e32 v32, v45, v32
	v_add_f32_e32 v32, v46, v32
	v_add_f32_e32 v32, v47, v32
	v_fmac_f32_e32 v32, v94, v36
	s_andn2_b64 exec, exec, s[50:51]
	s_cbranch_execnz .LBB0_255
	s_or_b64 exec, exec, s[50:51]
	s_branch .LBB0_252

.LBB0_831:
	s_or_b64 exec, exec, s[0:1]
	v_lshrrev_b32_e32 v0, 3, v69
	v_and_b32_e32 v1, 4, v69
	v_and_or_b32 v0, v0, 56, v1
	v_lshrrev_b32_e32 v0, 1, v0
	v_or_b32_e32 v87, v0, v106
	v_lshlrev_b32_e32 v1, 4, v69
	v_sub_u32_e64 v2, v0, 4 clamp
	v_sub_u32_e64 v0, v0, 3 clamp
	v_and_b32_e32 v36, 48, v1
	v_ashrrev_i32_e32 v35, 9, v69
	v_min_u32_e32 v91, 24, v2
	v_min_u32_e32 v0, 24, v0
	v_or_b32_e32 v32, v36, v107
	v_lshlrev_b32_e32 v1, 6, v87
	v_lshlrev_b32_e32 v34, 11, v35
	v_sub_u32_e32 v0, v0, v91
	v_or3_b32 v94, v1, v34, v32
	v_lshlrev_b32_e32 v1, 6, v33
	v_add_u32_e32 v110, 8, v0
	v_mov_b32_e32 v15, 0
	v_ashrrev_i32_e32 v95, 31, v94
	v_cmp_lt_i32_e32 vcc, 0, v110
	v_lshlrev_b32_e32 v96, 1, v1
	v_mov_b32_e32 v14, v15
	v_mov_b32_e32 v13, v15
	v_mov_b32_e32 v12, v15
	v_mov_b32_e32 v11, v15
	v_mov_b32_e32 v10, v15
	v_mov_b32_e32 v9, v15
	v_mov_b32_e32 v8, v15
	v_mov_b32_e32 v7, v15
	v_mov_b32_e32 v6, v15
	v_mov_b32_e32 v5, v15
	v_mov_b32_e32 v4, v15
	v_mov_b32_e32 v3, v15
	v_mov_b32_e32 v2, v15
	v_mov_b32_e32 v1, v15
	v_mov_b32_e32 v0, v15
	v_mov_b32_e32 v31, v15
	v_mov_b32_e32 v30, v15
	v_mov_b32_e32 v29, v15
	v_mov_b32_e32 v28, v15
	v_mov_b32_e32 v27, v15
	v_mov_b32_e32 v26, v15
	v_mov_b32_e32 v25, v15
	v_mov_b32_e32 v24, v15
	v_mov_b32_e32 v23, v15
	v_mov_b32_e32 v22, v15
	v_mov_b32_e32 v21, v15
	v_mov_b32_e32 v20, v15
	v_mov_b32_e32 v19, v15
	v_mov_b32_e32 v18, v15
	v_mov_b32_e32 v17, v15
	v_mov_b32_e32 v16, v15
	v_mov_b32_e32 v130, v15
	s_waitcnt lgkmcnt(0)
	s_and_saveexec_b64 s[2:3], vcc
	s_cbranch_execz .LBB0_828
	v_writelane_b32 v254, s2, 57
	v_max_i32_e32 v0, 4, v87
	v_add_u32_e32 v3, -4, v0
	v_writelane_b32 v254, s3, 58
	v_writelane_b32 v254, s16, 59
	v_mov_b32_e32 v97, v65
	v_mov_b32_e32 v89, v65
	v_writelane_b32 v254, s17, 60
	v_sub_u32_e64 v2, v36, 8 clamp
	v_readlane_b32 s0, v254, 55
	v_readlane_b32 s1, v254, 56
	v_min_u32_e32 v111, 24, v3
	v_mov_b32_e32 v130, 0
	v_mov_b64_e32 v[0:1], s[0:1]
	v_mad_i64_i32 v[0:1], s[0:1], v94, s85, v[0:1]
	v_lshl_add_u64 v[0:1], v[0:1], 0, v[96:97]
	v_lshl_add_u64 v[0:1], v[0:1], 0, v[88:89]
	global_load_dwordx4 v[48:51], v[0:1], off
	global_load_dwordx4 v[52:55], v[0:1], off offset:32
	global_load_dwordx4 v[56:59], v[0:1], off offset:64
	global_load_dwordx4 v[60:63], v[0:1], off offset:96
	v_min_u32_e32 v89, 32, v2
	v_or_b32_e32 v4, v89, v68
	v_max_i32_e32 v2, 8, v32
	v_sub_u32_e32 v5, v4, v32
	v_add_u32_e32 v2, -8, v2
	v_max_i32_e32 v5, -15, v5
	v_min_u32_e32 v2, 48, v2
	v_add_u32_e32 v5, 15, v5
	v_add_u32_e32 v3, 16, v2
	v_min_u32_e32 v114, 30, v5
	v_or_b32_e32 v5, 1, v4
	v_cmp_ge_u32_e64 s[8:9], v5, v2
	v_cmp_lt_u32_e64 s[10:11], v5, v3
	v_sub_u32_e32 v5, v5, v32
	v_max_i32_e32 v5, -15, v5
	v_add_u32_e32 v5, 15, v5
	v_min_u32_e32 v115, 30, v5
	v_or_b32_e32 v5, 2, v4
	v_cmp_ge_u32_e64 s[12:13], v5, v2
	v_cmp_lt_u32_e64 s[14:15], v5, v3
	v_sub_u32_e32 v5, v5, v32
	v_max_i32_e32 v5, -15, v5
	v_add_u32_e32 v5, 15, v5
	v_min_u32_e32 v116, 30, v5
	v_or_b32_e32 v5, 3, v4
	v_cmp_ge_u32_e64 s[16:17], v5, v2
	v_cmp_lt_u32_e64 s[18:19], v5, v3
	v_sub_u32_e32 v5, v5, v32
	v_max_i32_e32 v5, -15, v5
	v_add_u32_e32 v5, 15, v5
	v_min_u32_e32 v117, 30, v5
	v_add_u32_e32 v5, 8, v4
	v_cmp_ge_u32_e64 s[20:21], v5, v2
	v_cmp_lt_u32_e64 s[22:23], v5, v3
	v_sub_u32_e32 v5, v5, v32
	v_max_i32_e32 v5, -15, v5
	v_add_u32_e32 v5, 15, v5
	v_min_u32_e32 v118, 30, v5
	v_add_u32_e32 v5, 9, v4
	v_cmp_ge_u32_e64 s[24:25], v5, v2
	v_cmp_lt_u32_e64 s[26:27], v5, v3
	v_sub_u32_e32 v5, v5, v32
	v_max_i32_e32 v5, -15, v5
	v_add_u32_e32 v5, 15, v5
	v_min_u32_e32 v119, 30, v5
	v_add_u32_e32 v5, 10, v4
	v_cmp_ge_u32_e64 s[28:29], v5, v2
	v_cmp_lt_u32_e64 s[30:31], v5, v3
	v_sub_u32_e32 v5, v5, v32
	v_max_i32_e32 v5, -15, v5
	v_add_u32_e32 v5, 15, v5
	v_min_u32_e32 v120, 30, v5
	v_add_u32_e32 v5, 11, v4
	v_cmp_ge_u32_e64 s[34:35], v5, v2
	v_cmp_lt_u32_e64 s[36:37], v5, v3
	v_sub_u32_e32 v5, v5, v32
	v_max_i32_e32 v5, -15, v5
	v_add_u32_e32 v5, 15, v5
	v_min_u32_e32 v121, 30, v5
	v_add_u32_e32 v5, 16, v4
	v_cmp_ge_u32_e64 s[38:39], v5, v2
	v_sub_u32_e32 v5, v5, v32
	v_max_i32_e32 v5, -15, v5
	v_add_u32_e32 v5, 15, v5
	v_min_u32_e32 v122, 30, v5
	v_add_u32_e32 v5, 17, v4
	v_cmp_ge_u32_e64 s[42:43], v5, v2
	v_cmp_lt_u32_e64 s[44:45], v5, v3
	v_sub_u32_e32 v5, v5, v32
	v_max_i32_e32 v5, -15, v5
	v_add_u32_e32 v5, 15, v5
	v_min_u32_e32 v123, 30, v5
	v_add_u32_e32 v5, 18, v4
	v_cmp_ge_u32_e64 s[46:47], v5, v2
	v_cmp_lt_u32_e64 s[48:49], v5, v3
	v_sub_u32_e32 v5, v5, v32
	v_max_i32_e32 v5, -15, v5
	v_add_u32_e32 v5, 15, v5
	v_min_u32_e32 v124, 30, v5
	v_add_u32_e32 v5, 19, v4
	v_cmp_ge_u32_e64 s[50:51], v5, v2
	v_cmp_lt_u32_e64 s[52:53], v5, v3
	v_sub_u32_e32 v5, v5, v32
	v_max_i32_e32 v5, -15, v5
	v_add_u32_e32 v5, 15, v5
	v_min_u32_e32 v125, 30, v5
	v_add_u32_e32 v5, 24, v4
	v_cmp_ge_u32_e64 s[54:55], v5, v2
	v_cmp_lt_u32_e64 s[56:57], v5, v3
	v_sub_u32_e32 v5, v5, v32
	v_max_i32_e32 v5, -15, v5
	v_add_u32_e32 v5, 15, v5
	v_mad_i32_i24 v0, v35, 10, v33
	v_min_u32_e32 v126, 30, v5
	v_add_u32_e32 v5, 25, v4
	v_ashrrev_i32_e32 v1, 31, v0
	v_cmp_ge_u32_e64 s[58:59], v5, v2
	v_cmp_lt_u32_e64 s[60:61], v5, v3
	v_sub_u32_e32 v5, v5, v32
	v_lshlrev_b64 v[0:1], 18, v[0:1]
	v_max_i32_e32 v5, -15, v5
	v_lshl_add_u64 v[0:1], v[66:67], 0, v[0:1]
	s_mov_b64 s[0:1], 0x20000
	v_add_u32_e32 v5, 15, v5
	v_lshl_add_u64 v[98:99], v[0:1], 0, s[0:1]
	v_cmp_ge_u32_e64 s[0:1], v4, v2
	v_cmp_lt_u32_e64 s[6:7], v4, v3
	v_cmp_lt_u32_e64 s[40:41], v4, v2
	v_min_u32_e32 v127, 30, v5
	v_add_u32_e32 v5, 26, v4
	v_add_u32_e32 v4, 27, v4
	v_cmp_ge_u32_e64 s[62:63], v5, v2
	v_cmp_lt_u32_e64 s[64:65], v5, v3
	v_sub_u32_e32 v5, v5, v32
	v_cmp_ge_u32_e64 s[66:67], v4, v2
	v_sub_u32_e32 v2, v4, v32
	v_max_i32_e32 v5, -15, v5
	v_max_i32_e32 v2, -15, v2
	v_writelane_b32 v254, s0, 61
	v_add_u32_e32 v5, 15, v5
	v_add_u32_e32 v2, 15, v2
	v_or_b32_e32 v112, v34, v104
	v_add_u32_e32 v113, 8, v111
	v_writelane_b32 v254, s1, 62
	v_min_u32_e32 v128, 30, v5
	v_cmp_lt_u32_e64 s[68:69], v4, v3
	v_min_u32_e32 v129, 30, v2
	v_lshl_add_u64 v[100:101], v[70:71], 0, v[96:97]
	v_lshl_add_u64 v[102:103], v[0:1], 0, v[92:93]
	s_mov_b32 s33, 0
	v_mov_b32_e32 v97, 0xf149f2ca
	s_mov_b64 s[0:1], 0
	v_mov_b32_e32 v0, 0
	v_mov_b32_e32 v1, v130
	v_mov_b32_e32 v2, v130
	v_mov_b32_e32 v3, v130
	v_mov_b32_e32 v4, v130
	v_mov_b32_e32 v5, v130
	v_mov_b32_e32 v6, v130
	v_mov_b32_e32 v7, v130
	v_mov_b32_e32 v8, v130
	v_mov_b32_e32 v9, v130
	v_mov_b32_e32 v10, v130
	v_mov_b32_e32 v11, v130
	v_mov_b32_e32 v12, v130
	v_mov_b32_e32 v13, v130
	v_mov_b32_e32 v14, v130
	v_mov_b32_e32 v15, v130
	v_mov_b32_e32 v16, 0
	v_mov_b32_e32 v17, v130
	v_mov_b32_e32 v18, v130
	v_mov_b32_e32 v19, v130
	v_mov_b32_e32 v20, v130
	v_mov_b32_e32 v21, v130
	v_mov_b32_e32 v22, v130
	v_mov_b32_e32 v23, v130
	v_mov_b32_e32 v24, v130
	v_mov_b32_e32 v25, v130
	v_mov_b32_e32 v26, v130
	v_mov_b32_e32 v27, v130
	v_mov_b32_e32 v28, v130
	v_mov_b32_e32 v29, v130
	v_mov_b32_e32 v30, v130
	v_mov_b32_e32 v31, v130
	s_mov_b64 s[98:99], 0x88000
	v_add_u32_e32 v32, s33, v91
	v_lshl_or_b32 v64, v32, 6, v89
	v_sub_u32_e32 v33, v32, v87
	v_cmp_ge_u32_e32 vcc, v32, v111
	v_cmp_lt_u32_e64 s[2:3], v32, v113
	v_add_u32_e32 v32, v112, v64
	v_max_i32_e32 v33, -7, v33
	s_and_b64 s[86:87], vcc, s[2:3]
	v_mad_i64_i32 v[36:37], s[2:3], v32, s85, v[100:101]
	global_load_dwordx4 v[200:203], v[36:37], off offset:1024
	global_load_dwordx4 v[204:207], v[36:37], off offset:1056
	global_load_dwordx4 v[208:211], v[36:37], off offset:1088
	global_load_dwordx4 v[212:215], v[36:37], off offset:1120
.LBB0_833:
	v_add_u32_e32 v32, s33, v91
	v_lshl_or_b32 v64, v32, 6, v89
	v_sub_u32_e32 v33, v32, v87
	v_cmp_ge_u32_e32 vcc, v32, v111
	v_cmp_lt_u32_e64 s[2:3], v32, v113
	v_add_u32_e32 v32, v112, v64
	v_max_i32_e32 v33, -7, v33
	s_and_b64 s[86:87], vcc, s[2:3]
	v_mad_i64_i32 v[36:37], s[2:3], v32, s85, v[100:101]
	v_add_u32_e32 v38, 7, v33
	v_lshl_add_u64 v[218:219], v[36:37], 0, s[98:99]
	v_min_u32_e32 v36, 14, v38
	s_movk_i32 vcc_lo, 0x7c
	v_mad_u32_u24 v131, v36, vcc_lo, v105
	v_lshl_add_u32 v144, v114, 2, v131
	v_lshl_add_u32 v145, v115, 2, v131
	ds_read_b32 v144, v144
	ds_read_b32 v145, v145
	v_readlane_b32 s2, v254, 61
	v_lshl_add_u32 v146, v116, 2, v131
	v_lshl_add_u32 v147, v117, 2, v131
	v_lshl_add_u32 v148, v118, 2, v131
	v_readlane_b32 s3, v254, 62
	v_lshl_add_u32 v149, v119, 2, v131
	v_lshl_add_u32 v150, v120, 2, v131
	v_lshl_add_u32 v151, v121, 2, v131
	v_lshl_add_u32 v152, v122, 2, v131
	s_and_b64 s[2:3], s[86:87], s[2:3]
	s_and_b64 s[4:5], s[86:87], s[8:9]
	s_and_b64 s[96:97], s[86:87], s[12:13]
	s_and_b64 s[94:95], s[86:87], s[16:17]
	s_and_b64 s[4:5], s[4:5], s[10:11]
	s_and_b64 s[2:3], s[2:3], s[6:7]
	s_and_b64 s[92:93], s[86:87], s[20:21]
	s_and_b64 s[90:91], s[86:87], s[24:25]
	v_lshl_add_u32 v153, v123, 2, v131
	v_lshl_add_u32 v154, v124, 2, v131
	v_lshl_add_u32 v155, v125, 2, v131
	v_lshl_add_u32 v156, v126, 2, v131
	v_lshl_add_u32 v157, v127, 2, v131
	v_lshl_add_u32 v158, v128, 2, v131
	v_lshl_add_u32 v131, v129, 2, v131
	s_and_b64 s[96:97], s[96:97], s[14:15]
	s_and_b64 s[94:95], s[94:95], s[18:19]
	s_and_b64 s[88:89], s[86:87], s[28:29]
	s_and_b64 s[70:71], s[86:87], s[34:35]
	s_and_b64 s[92:93], s[92:93], s[22:23]
	s_and_b64 s[90:91], s[90:91], s[26:27]
	s_and_b64 s[72:73], s[86:87], s[38:39]
	s_and_b64 s[74:75], s[86:87], s[42:43]
	s_and_b64 s[88:89], s[88:89], s[30:31]
	s_and_b64 s[70:71], s[70:71], s[36:37]
	s_and_b64 s[76:77], s[86:87], s[46:47]
	s_and_b64 s[78:79], s[86:87], s[50:51]
	s_and_b64 s[72:73], s[72:73], s[40:41]
	s_and_b64 s[74:75], s[74:75], s[44:45]
	s_and_b64 s[80:81], s[86:87], s[54:55]
	s_and_b64 s[82:83], s[86:87], s[58:59]
	s_and_b64 s[76:77], s[76:77], s[48:49]
	s_and_b64 s[78:79], s[78:79], s[52:53]
	s_and_b64 s[84:85], s[86:87], s[62:63]
	s_and_b64 s[86:87], s[86:87], s[66:67]
	s_and_b64 s[80:81], s[80:81], s[56:57]
	s_and_b64 s[82:83], s[82:83], s[60:61]
	s_and_b64 s[84:85], s[84:85], s[64:65]
	s_and_b64 s[86:87], s[86:87], s[68:69]
	s_add_i32 s33, s33, 1
	v_cmp_ge_i32_e32 vcc, s33, v110
	s_or_b64 s[0:1], vcc, s[0:1]
	s_waitcnt vmcnt(3)
	v_mfma_f32_32x32x16_bf16 v[32:47], v[200:203], v[48:51], 0
	s_waitcnt vmcnt(2)
	v_mfma_f32_32x32x16_bf16 v[32:47], v[204:207], v[52:55], v[32:47]
	ds_read_b32 v132, v146
	ds_read_b32 v133, v147
	ds_read_b32 v134, v148
	ds_read_b32 v135, v149
	ds_read_b32 v146, v150
	ds_read_b32 v147, v151
	ds_read_b32 v148, v152
	s_waitcnt vmcnt(1)
	v_mfma_f32_32x32x16_bf16 v[32:47], v[208:211], v[56:59], v[32:47]
	ds_read_b32 v136, v153
	ds_read_b32 v137, v154
	ds_read_b32 v138, v155
	ds_read_b32 v139, v156
	ds_read_b32 v149, v157
	ds_read_b32 v150, v158
	ds_read_b32 v131, v131
	s_waitcnt vmcnt(0)
	v_mfma_f32_32x32x16_bf16 v[32:47], v[212:215], v[60:63], v[32:47]
	s_waitcnt lgkmcnt(14)
	s_nop 10
	v_add_f32_e32 v32, v32, v144
	v_add_f32_e32 v33, v33, v145
	s_waitcnt lgkmcnt(13)
	v_add_f32_e32 v34, v34, v132
	s_waitcnt lgkmcnt(12)
	v_add_f32_e32 v132, v35, v133
	v_max_f32_e32 v35, 0xf149f2ca, v32
	s_waitcnt lgkmcnt(11)
	v_add_f32_e32 v133, v36, v134
	v_cndmask_b32_e64 v36, v109, v33, s[4:5]
	v_cndmask_b32_e64 v35, v109, v35, s[2:3]
	s_waitcnt lgkmcnt(10)
	v_add_f32_e32 v134, v37, v135
	s_waitcnt lgkmcnt(9)
	v_add_f32_e32 v135, v38, v146
	v_cndmask_b32_e64 v37, v109, v34, s[96:97]
	v_cndmask_b32_e64 v38, v109, v132, s[94:95]
	v_max_f32_e32 v35, v35, v36
	s_waitcnt lgkmcnt(8)
	v_add_f32_e32 v140, v39, v147
	s_waitcnt lgkmcnt(7)
	v_add_f32_e32 v141, v40, v148
	v_cndmask_b32_e64 v39, v109, v133, s[92:93]
	v_cndmask_b32_e64 v40, v109, v134, s[90:91]
	v_max3_f32 v35, v35, v37, v38
	s_waitcnt lgkmcnt(6)
	v_add_f32_e32 v136, v41, v136
	s_waitcnt lgkmcnt(5)
	v_add_f32_e32 v137, v42, v137
	v_cndmask_b32_e64 v41, v109, v135, s[88:89]
	v_cndmask_b32_e64 v42, v109, v140, s[70:71]
	v_max3_f32 v35, v35, v39, v40
	s_waitcnt lgkmcnt(4)
	v_add_f32_e32 v138, v43, v138
	s_waitcnt lgkmcnt(3)
	v_add_f32_e32 v139, v44, v139
	v_cndmask_b32_e64 v43, v109, v141, s[72:73]
	v_cndmask_b32_e64 v44, v109, v136, s[74:75]
	v_max3_f32 v35, v35, v41, v42
	s_waitcnt lgkmcnt(2)
	v_add_f32_e32 v142, v45, v149
	s_waitcnt lgkmcnt(1)
	v_add_f32_e32 v143, v46, v150
	v_cndmask_b32_e64 v45, v109, v137, s[76:77]
	v_cndmask_b32_e64 v46, v109, v138, s[78:79]
	v_max3_f32 v35, v35, v43, v44
	s_waitcnt lgkmcnt(0)
	v_add_f32_e32 v131, v47, v131
	v_cndmask_b32_e64 v47, v109, v139, s[80:81]
	v_cndmask_b32_e64 v144, v109, v142, s[82:83]
	v_max3_f32 v35, v35, v45, v46
	v_cndmask_b32_e64 v145, v109, v143, s[84:85]
	v_cndmask_b32_e64 v146, v109, v131, s[86:87]
	v_max3_f32 v35, v35, v47, v144
	v_max3_f32 v35, v35, v145, v146
	v_mov_b32_e32 v36, v35
	s_nop 1
	v_permlane32_swap_b32_e32 v35, v36
	v_max3_f32 v144, v97, v35, v36
	v_sub_f32_e32 v32, v32, v144
	v_mul_f32_e32 v32, 0x3fb8aa3b, v32
	v_exp_f32_e32 v32, v32
	v_mov_b32_e32 v148, v130
	v_sub_f32_e32 v130, v132, v144
	v_sub_f32_e32 v132, v133, v144
	v_cndmask_b32_e64 v145, 0, v32, s[2:3]
	v_sub_f32_e32 v32, v33, v144
	v_mul_f32_e32 v32, 0x3fb8aa3b, v32
	v_exp_f32_e32 v32, v32
	v_sub_f32_e32 v133, v134, v144
	v_sub_f32_e32 v134, v135, v144
	v_sub_f32_e32 v135, v140, v144
	v_cndmask_b32_e64 v146, 0, v32, s[4:5]
	v_sub_f32_e32 v32, v34, v144
	v_mul_f32_e32 v32, 0x3fb8aa3b, v32
	v_exp_f32_e32 v32, v32
	v_sub_f32_e32 v131, v131, v144
	v_mul_f32_e32 v130, 0x3fb8aa3b, v130
	v_mul_f32_e32 v132, 0x3fb8aa3b, v132
	v_cndmask_b32_e64 v147, 0, v32, s[96:97]
	v_lshlrev_b64 v[32:33], 1, v[64:65]
	v_lshl_add_u64 v[38:39], v[102:103], 0, v[32:33]
	v_lshl_add_u64 v[36:37], v[98:99], 0, v[32:33]
	global_load_dwordx2 v[32:33], v[38:39], off
	global_load_dwordx2 v[34:35], v[38:39], off offset:16
	v_lshl_add_u64 v[46:47], v[36:37], 0, v[92:93]
	global_load_dwordx2 v[36:37], v[38:39], off offset:32
	s_nop 0
	global_load_dwordx2 v[38:39], v[38:39], off offset:48
	s_nop 0
	global_load_dwordx2 v[40:41], v[46:47], off
	global_load_dwordx2 v[42:43], v[46:47], off offset:16
	global_load_dwordx2 v[44:45], v[46:47], off offset:32
	s_nop 0
	global_load_dwordx2 v[46:47], v[46:47], off offset:48
	global_load_dwordx4 v[200:203], v[218:219], off offset:1024
	global_load_dwordx4 v[204:207], v[218:219], off offset:1056
	global_load_dwordx4 v[208:211], v[218:219], off offset:1088
	global_load_dwordx4 v[212:215], v[218:219], off offset:1120
	v_sub_f32_e32 v64, v97, v144
	v_mul_f32_e32 v133, 0x3fb8aa3b, v133
	v_mul_f32_e32 v134, 0x3fb8aa3b, v134
	v_mul_f32_e32 v135, 0x3fb8aa3b, v135
	v_mul_f32_e32 v64, 0x3fb8aa3b, v64
	v_mul_f32_e32 v131, 0x3fb8aa3b, v131
	v_exp_f32_e32 v130, v130
	v_exp_f32_e32 v132, v132
	v_exp_f32_e32 v133, v133
	v_exp_f32_e32 v134, v134
	v_exp_f32_e32 v135, v135
	v_exp_f32_e32 v131, v131
	v_exp_f32_e32 v64, v64
	v_sub_f32_e32 v140, v141, v144
	v_sub_f32_e32 v136, v136, v144
	v_sub_f32_e32 v137, v137, v144
	v_sub_f32_e32 v138, v138, v144
	v_sub_f32_e32 v139, v139, v144
	v_sub_f32_e32 v141, v142, v144
	v_sub_f32_e32 v142, v143, v144
	v_mov_b32_e32 v97, v144
	v_cndmask_b32_e64 v143, 0, v130, s[94:95]
	v_cndmask_b32_e64 v144, 0, v132, s[92:93]
	v_cndmask_b32_e64 v149, 0, v133, s[90:91]
	v_cndmask_b32_e64 v134, 0, v134, s[88:89]
	v_cndmask_b32_e64 v135, 0, v135, s[70:71]
	v_cndmask_b32_e64 v150, 0, v131, s[86:87]
	v_pk_mul_f32 v[14:15], v[14:15], v[64:65] op_sel_hi:[1,0]
	v_pk_mul_f32 v[12:13], v[12:13], v[64:65] op_sel_hi:[1,0]
	v_pk_mul_f32 v[10:11], v[10:11], v[64:65] op_sel_hi:[1,0]
	v_pk_mul_f32 v[8:9], v[8:9], v[64:65] op_sel_hi:[1,0]
	v_pk_mul_f32 v[6:7], v[6:7], v[64:65] op_sel_hi:[1,0]
	v_pk_mul_f32 v[4:5], v[4:5], v[64:65] op_sel_hi:[1,0]
	v_pk_mul_f32 v[2:3], v[2:3], v[64:65] op_sel_hi:[1,0]
	v_pk_mul_f32 v[0:1], v[0:1], v[64:65] op_sel_hi:[1,0]
	v_cvt_pk_bf16_f32 v130, v145, v146
	v_cvt_pk_bf16_f32 v131, v147, v143
	v_cvt_pk_bf16_f32 v132, v144, v149
	v_cvt_pk_bf16_f32 v133, v134, v135
	v_mul_f32_e32 v140, 0x3fb8aa3b, v140
	v_mul_f32_e32 v136, 0x3fb8aa3b, v136
	s_waitcnt vmcnt(10)
	v_mfma_f32_32x32x16_bf16 v[0:15], v[32:35], v[130:133], v[0:15]
	v_mul_f32_e32 v137, 0x3fb8aa3b, v137
	v_mul_f32_e32 v138, 0x3fb8aa3b, v138
	v_mul_f32_e32 v139, 0x3fb8aa3b, v139
	v_mul_f32_e32 v141, 0x3fb8aa3b, v141
	v_mul_f32_e32 v142, 0x3fb8aa3b, v142
	v_exp_f32_e32 v140, v140
	v_exp_f32_e32 v136, v136
	v_exp_f32_e32 v137, v137
	v_exp_f32_e32 v138, v138
	v_exp_f32_e32 v139, v139
	v_exp_f32_e32 v141, v141
	v_exp_f32_e32 v142, v142
	v_pk_mul_f32 v[30:31], v[30:31], v[64:65] op_sel_hi:[1,0]
	v_pk_mul_f32 v[28:29], v[28:29], v[64:65] op_sel_hi:[1,0]
	v_pk_mul_f32 v[26:27], v[26:27], v[64:65] op_sel_hi:[1,0]
	v_pk_mul_f32 v[24:25], v[24:25], v[64:65] op_sel_hi:[1,0]
	v_pk_mul_f32 v[22:23], v[22:23], v[64:65] op_sel_hi:[1,0]
	v_pk_mul_f32 v[20:21], v[20:21], v[64:65] op_sel_hi:[1,0]
	v_pk_mul_f32 v[18:19], v[18:19], v[64:65] op_sel_hi:[1,0]
	v_pk_mul_f32 v[16:17], v[16:17], v[64:65] op_sel_hi:[1,0]
	v_cndmask_b32_e64 v140, 0, v140, s[72:73]
	v_cndmask_b32_e64 v136, 0, v136, s[74:75]
	s_waitcnt vmcnt(6)
	v_mfma_f32_32x32x16_bf16 v[16:31], v[40:43], v[130:133], v[16:31]
	v_add_f32_e32 v40, 0, v145
	v_cndmask_b32_e64 v137, 0, v137, s[76:77]
	v_cndmask_b32_e64 v138, 0, v138, s[78:79]
	v_cndmask_b32_e64 v139, 0, v139, s[80:81]
	v_cndmask_b32_e64 v141, 0, v141, s[82:83]
	v_cndmask_b32_e64 v142, 0, v142, s[84:85]
	v_add_f32_e32 v40, v146, v40
	v_cvt_pk_bf16_f32 v32, v140, v136
	v_cvt_pk_bf16_f32 v33, v137, v138
	v_cvt_pk_bf16_f32 v34, v139, v141
	v_cvt_pk_bf16_f32 v35, v142, v150
	v_add_f32_e32 v40, v147, v40
	s_movk_i32 s85, 0x2200
	v_mfma_f32_32x32x16_bf16 v[0:15], v[36:39], v[32:35], v[0:15]
	v_add_f32_e32 v36, v143, v40
	v_add_f32_e32 v36, v144, v36
	v_add_f32_e32 v36, v149, v36
	v_add_f32_e32 v36, v134, v36
	v_add_f32_e32 v36, v135, v36
	v_add_f32_e32 v36, v140, v36
	v_add_f32_e32 v36, v136, v36
	s_waitcnt vmcnt(4)
	v_mfma_f32_32x32x16_bf16 v[16:31], v[44:47], v[32:35], v[16:31]
	v_add_f32_e32 v32, v137, v36
	v_add_f32_e32 v32, v138, v32
	v_add_f32_e32 v32, v139, v32
	v_add_f32_e32 v32, v141, v32
	v_add_f32_e32 v32, v142, v32
	v_add_f32_e32 v130, v150, v32
	v_fmac_f32_e32 v130, v148, v64
	s_andn2_b64 exec, exec, s[0:1]
	s_cbranch_execnz .LBB0_833
	s_or_b64 exec, exec, s[0:1]
	v_readlane_b32 s68, v254, 25
	v_readlane_b32 s72, v254, 29
	v_readlane_b32 s73, v254, 30
	v_readlane_b32 s88, v254, 47
	v_readlane_b32 s70, v254, 27
	v_readlane_b32 s71, v254, 28
	v_readlane_b32 s82, v254, 39
	v_readlane_b32 s83, v254, 40
	v_readlane_b32 s90, v254, 45
	v_readlane_b32 s89, v254, 48
	v_readlane_b32 s72, v254, 51
	v_readlane_b32 s92, v254, 53
	v_readlane_b32 s16, v254, 59
	v_readlane_b32 s18, v254, 41
	v_readlane_b32 s20, v254, 43
	v_readlane_b32 s2, v254, 57
	s_mov_b64 s[70:71], s[82:83]
	v_readlane_b32 s91, v254, 46
	s_mov_b32 s84, s72
	v_readlane_b32 s89, v254, 49
	v_readlane_b32 s93, v254, 54
	v_readlane_b32 s17, v254, 60
	v_readlane_b32 s19, v254, 42
	v_readlane_b32 s21, v254, 44
	v_readlane_b32 s3, v254, 58
	v_readlane_b32 s69, v254, 26
	v_readlane_b32 s74, v254, 31
	v_readlane_b32 s75, v254, 32
	v_readlane_b32 s76, v254, 33
	v_readlane_b32 s77, v254, 34
	v_readlane_b32 s78, v254, 35
	v_readlane_b32 s79, v254, 36
	v_readlane_b32 s80, v254, 37
	v_readlane_b32 s81, v254, 38
	v_readlane_b32 s73, v254, 52
	s_branch .LBB0_828

.LBB0_838:
	v_lshrrev_b32_e32 v0, 3, v88
	v_and_b32_e32 v2, 4, v88
	v_and_b32_e32 v1, 6, v0
	v_and_or_b32 v0, v0, 8, v2
	v_lshrrev_b32_e32 v2, 1, v88
	v_ashrrev_i32_e32 v33, 8, v88
	v_and_b32_e32 v34, 4, v2
	v_lshrrev_b32_e32 v0, 2, v0
	v_and_or_b32 v35, v33, -8, v1
	v_and_b32_e32 v1, 0x780, v88
	v_or_b32_e32 v36, v0, v34
	v_lshlrev_b32_e32 v0, 5, v88
	v_and_or_b32 v0, v0, s54, v1
	v_lshlrev_b32_e32 v1, 10, v35
	v_or3_b32 v78, v0, v89, v1
	v_lshrrev_b32_e32 v0, 5, v0
	v_min_u32_e32 v2, 59, v0
	v_lshlrev_b32_e32 v1, 6, v36
	v_sub_u32_e64 v71, v0, 4 clamp
	v_add_u32_e32 v73, 5, v2
	v_ashrrev_i32_e32 v79, 31, v78
	v_cmp_lt_u32_e32 vcc, v71, v73
	v_lshlrev_b32_e32 v80, 1, v1
	v_mov_b32_e32 v15, v65
	v_mov_b32_e32 v14, v65
	v_mov_b32_e32 v13, v65
	v_mov_b32_e32 v12, v65
	v_mov_b32_e32 v11, v65
	v_mov_b32_e32 v10, v65
	v_mov_b32_e32 v9, v65
	v_mov_b32_e32 v8, v65
	v_mov_b32_e32 v7, v65
	v_mov_b32_e32 v6, v65
	v_mov_b32_e32 v5, v65
	v_mov_b32_e32 v4, v65
	v_mov_b32_e32 v3, v65
	v_mov_b32_e32 v2, v65
	v_mov_b32_e32 v1, v65
	v_mov_b32_e32 v0, v65
	v_mov_b32_e32 v31, v65
	v_mov_b32_e32 v30, v65
	v_mov_b32_e32 v29, v65
	v_mov_b32_e32 v28, v65
	v_mov_b32_e32 v27, v65
	v_mov_b32_e32 v26, v65
	v_mov_b32_e32 v25, v65
	v_mov_b32_e32 v24, v65
	v_mov_b32_e32 v23, v65
	v_mov_b32_e32 v22, v65
	v_mov_b32_e32 v21, v65
	v_mov_b32_e32 v20, v65
	v_mov_b32_e32 v19, v65
	v_mov_b32_e32 v18, v65
	v_mov_b32_e32 v17, v65
	v_mov_b32_e32 v16, v65
	v_mov_b32_e32 v32, v90
	s_and_saveexec_b64 s[48:49], vcc
	s_cbranch_execz .LBB0_837
	v_mov_b64_e32 v[0:1], s[38:39]
	v_mad_i64_i32 v[0:1], s[0:1], v78, s55, v[0:1]
	v_mov_b32_e32 v81, v65
	v_lshl_add_u64 v[0:1], v[0:1], 0, v[80:81]
	v_mov_b32_e32 v77, v65
	v_lshl_add_u64 v[0:1], v[0:1], 0, v[76:77]
	global_load_dwordx4 v[48:51], v[0:1], off offset:3072
	global_load_dwordx4 v[52:55], v[0:1], off offset:3104
	global_load_dwordx4 v[56:59], v[0:1], off offset:3136
	global_load_dwordx4 v[60:63], v[0:1], off offset:3168
	v_readlane_b32 s0, v254, 6
	v_lshlrev_b32_e32 v0, 2, v36
	v_readlane_b32 s12, v254, 18
	v_readlane_b32 s13, v254, 19
	v_lshrrev_b32_e32 v1, 1, v35
	v_mul_i32_i24_e32 v1, 10, v1
	v_mov_b32_e32 v69, v65
	v_lshlrev_b32_e32 v64, 5, v34
	v_lshl_add_u64 v[82:83], s[38:39], 0, v[64:65]
	global_load_dword v81, v0, s[12:13] offset:32
	v_and_b32_e32 v0, 0x60, v92
	v_and_or_b32 v2, v88, s53, v0
	v_lshrrev_b32_e32 v0, 5, v2
	v_min_u32_e32 v0, 4, v0
	v_lshlrev_b32_e32 v3, 5, v0
	v_lshlrev_b32_e32 v0, 7, v88
	v_and_b32_e32 v5, 0x1800, v0
	v_lshrrev_b32_e32 v0, 2, v34
	v_or_b32_e32 v0, v1, v0
	v_add_u32_e32 v0, 8, v0
	v_ashrrev_i32_e32 v1, 31, v0
	v_lshlrev_b64 v[0:1], 18, v[0:1]
	v_lshl_add_u64 v[0:1], v[66:67], 0, v[0:1]
	v_lshl_add_u64 v[84:85], v[0:1], 0, v[68:69]
	v_lshlrev_b32_e32 v0, 10, v33
	v_and_b32_e32 v0, 0xffffe000, v0
	v_or3_b32 v0, v0, v5, v2
	v_sub_u32_e32 v4, v2, v3
	v_sub_u32_e32 v69, v0, v3
	v_mov_b32_e32 v0, 0
	v_add_u32_e32 v75, v91, v3
	v_lshl_add_u64 v[86:87], v[84:85], 0, s[40:41]
	s_mov_b64 s[50:51], 0
	v_mov_b32_e32 v64, v4
	v_mov_b32_e32 v32, v90
	v_mov_b32_e32 v1, v0
	v_mov_b32_e32 v2, v0
	v_mov_b32_e32 v3, v0
	v_mov_b32_e32 v4, v0
	v_mov_b32_e32 v5, v0
	v_mov_b32_e32 v6, v0
	v_mov_b32_e32 v7, v0
	v_mov_b32_e32 v8, v0
	v_mov_b32_e32 v9, v0
	v_mov_b32_e32 v10, v0
	v_mov_b32_e32 v11, v0
	v_mov_b32_e32 v12, v0
	v_mov_b32_e32 v13, v0
	v_mov_b32_e32 v14, v0
	v_mov_b32_e32 v15, v0
	v_mov_b32_e32 v16, v0
	v_mov_b32_e32 v17, v0
	v_mov_b32_e32 v18, v0
	v_mov_b32_e32 v19, v0
	v_mov_b32_e32 v20, v0
	v_mov_b32_e32 v21, v0
	v_mov_b32_e32 v22, v0
	v_mov_b32_e32 v23, v0
	v_mov_b32_e32 v24, v0
	v_mov_b32_e32 v25, v0
	v_mov_b32_e32 v26, v0
	v_mov_b32_e32 v27, v0
	v_mov_b32_e32 v28, v0
	v_mov_b32_e32 v29, v0
	v_mov_b32_e32 v30, v0
	v_mov_b32_e32 v31, v0
	v_readlane_b32 s1, v254, 7
	v_readlane_b32 s2, v254, 8
	v_readlane_b32 s3, v254, 9
	v_readlane_b32 s4, v254, 10
	v_readlane_b32 s5, v254, 11
	v_readlane_b32 s6, v254, 12
	v_readlane_b32 s7, v254, 13
	v_readlane_b32 s8, v254, 14
	v_readlane_b32 s9, v254, 15
	v_readlane_b32 s10, v254, 16
	v_readlane_b32 s11, v254, 17
	v_readlane_b32 s14, v254, 20
	v_readlane_b32 s15, v254, 21
	s_mov_b64 s[98:99], 0x44000
	v_add_u32_e32 v216, v89, v69
	v_mad_i64_i32 v[216:217], s[0:1], v216, s55, v[82:83]
	v_lshl_add_u64 v[216:217], v[216:217], 0, v[76:77]
	v_add_co_u32_e64 v218, s[0:1], s33, v216
	v_lshl_add_u64 v[220:221], v[216:217], 0, s[42:43]
	s_nop 0
	v_addc_co_u32_e64 v219, s[0:1], 0, v217, s[0:1]
	global_load_dwordx4 v[200:203], v[218:219], off
	global_load_dwordx4 v[204:207], v[220:221], off offset:32
	global_load_dwordx4 v[208:211], v[220:221], off offset:64
	global_load_dwordx4 v[212:215], v[220:221], off offset:96
